# P1 GEMM loop: LDS-DMA loads use scalar base + 32-bit lane offset (saddr form) instead of per-load 64-bit VALU adds
# speedup vs baseline: 1.0729x; 1.0077x over previous
.LBB0_181:
	ds_read_b128 v[144:147], v157
	ds_read_b128 v[148:151], v157 offset:1024
	ds_read_b128 v[162:165], v157 offset:2048
	ds_read_b128 v[166:169], v157 offset:3072
	s_add_u32 s30, s28, 0xfff80080
	s_addc_u32 s31, s29, -1
	s_cmp_eq_u32 s54, 28
	s_cselect_b32 s35, s2, s31
	s_cselect_b32 s34, s3, s30
	s_cselect_b32 s31, s7, s27
	s_cselect_b32 s30, s9, s11
	s_add_i32 m0, s39, 0xc000
	ds_read_b128 v[170:173], v158
	ds_read_b128 v[174:177], v158 offset:1024
	ds_read_b128 v[178:181], v158 offset:2048
	ds_read_b128 v[186:189], v158 offset:3072
	ds_read_b128 v[194:197], v158 offset:4096
	ds_read_b128 v[198:201], v158 offset:5120
	ds_read_b128 v[202:205], v158 offset:6144
	ds_read_b128 v[206:209], v158 offset:7168
	global_load_lds_dwordx4 v136, s[28:29]
	s_add_i32 m0, s39, 0xe000
	s_nop 0
	global_load_lds_dwordx4 v138, s[28:29]
	s_waitcnt lgkmcnt(8)
	s_barrier
	s_waitcnt lgkmcnt(0)
	s_setprio 1
	s_waitcnt lgkmcnt(0)
	v_mfma_f32_16x16x32_bf16 v[124:127], v[144:147], v[170:173], v[124:127]
	v_mfma_f32_16x16x32_bf16 v[120:123], v[162:165], v[170:173], v[120:123]
	v_mfma_f32_16x16x32_bf16 v[108:111], v[144:147], v[178:181], v[108:111]
	v_mfma_f32_16x16x32_bf16 v[104:107], v[162:165], v[178:181], v[104:107]
	v_mfma_f32_16x16x32_bf16 v[92:95], v[144:147], v[194:197], v[92:95]
	v_mfma_f32_16x16x32_bf16 v[88:91], v[162:165], v[194:197], v[88:91]
	v_mfma_f32_16x16x32_bf16 v[76:79], v[144:147], v[202:205], v[76:79]
	v_mfma_f32_16x16x32_bf16 v[72:75], v[162:165], v[202:205], v[72:75]
	v_mfma_f32_16x16x32_bf16 v[124:127], v[148:151], v[174:177], v[124:127]
	v_mfma_f32_16x16x32_bf16 v[120:123], v[166:169], v[174:177], v[120:123]
	v_mfma_f32_16x16x32_bf16 v[108:111], v[148:151], v[186:189], v[108:111]
	v_mfma_f32_16x16x32_bf16 v[104:107], v[166:169], v[186:189], v[104:107]
	v_mfma_f32_16x16x32_bf16 v[92:95], v[148:151], v[198:201], v[92:95]
	v_mfma_f32_16x16x32_bf16 v[88:91], v[166:169], v[198:201], v[88:91]
	v_mfma_f32_16x16x32_bf16 v[76:79], v[148:151], v[206:209], v[76:79]
	v_mfma_f32_16x16x32_bf16 v[72:75], v[166:169], v[206:209], v[72:75]
	s_setprio 0
	s_barrier
	s_add_i32 s55, s48, s38
	s_add_u32 s58, s30, s0
	s_addc_u32 s59, s31, s1
	s_mov_b32 m0, s55
	ds_read_b128 v[210:213], v159
	ds_read_b128 v[214:217], v159 offset:1024
	ds_read_b128 v[218:221], v159 offset:2048
	ds_read_b128 v[222:225], v159 offset:3072
	global_load_lds_dwordx4 v130, s[30:31]
	s_add_i32 m0, s55, 0x2000
	s_nop 0
	global_load_lds_dwordx4 v134, s[30:31]
	s_barrier
	s_waitcnt lgkmcnt(0)
	s_setprio 1
	s_waitcnt lgkmcnt(0)
	v_mfma_f32_16x16x32_bf16 v[116:119], v[210:213], v[170:173], v[116:119]
	v_mfma_f32_16x16x32_bf16 v[112:115], v[218:221], v[170:173], v[112:115]
	v_mfma_f32_16x16x32_bf16 v[100:103], v[210:213], v[178:181], v[100:103]
	v_mfma_f32_16x16x32_bf16 v[96:99], v[218:221], v[178:181], v[96:99]
	v_mfma_f32_16x16x32_bf16 v[84:87], v[210:213], v[194:197], v[84:87]
	v_mfma_f32_16x16x32_bf16 v[80:83], v[218:221], v[194:197], v[80:83]
	v_mfma_f32_16x16x32_bf16 v[68:71], v[210:213], v[202:205], v[68:71]
	v_mfma_f32_16x16x32_bf16 v[64:67], v[218:221], v[202:205], v[64:67]
	v_mfma_f32_16x16x32_bf16 v[116:119], v[214:217], v[174:177], v[116:119]
	v_mfma_f32_16x16x32_bf16 v[112:115], v[222:225], v[174:177], v[112:115]
	v_mfma_f32_16x16x32_bf16 v[100:103], v[214:217], v[186:189], v[100:103]
	v_mfma_f32_16x16x32_bf16 v[96:99], v[222:225], v[186:189], v[96:99]
	v_mfma_f32_16x16x32_bf16 v[84:87], v[214:217], v[198:201], v[84:87]
	v_mfma_f32_16x16x32_bf16 v[80:83], v[222:225], v[198:201], v[80:83]
	v_mfma_f32_16x16x32_bf16 v[68:71], v[214:217], v[206:209], v[68:71]
	v_mfma_f32_16x16x32_bf16 v[64:67], v[222:225], v[206:209], v[64:67]
	s_setprio 0
	s_mov_b32 m0, s39
	s_add_u32 s60, s34, s0
	s_addc_u32 s61, s35, s1
	s_barrier
	ds_read_b128 v[170:173], v158 offset:16384
	ds_read_b128 v[174:177], v158 offset:17408
	ds_read_b128 v[178:181], v158 offset:18432
	ds_read_b128 v[186:189], v158 offset:19456
	ds_read_b128 v[194:197], v158 offset:20480
	ds_read_b128 v[198:201], v158 offset:21504
	ds_read_b128 v[202:205], v158 offset:22528
	ds_read_b128 v[206:209], v158 offset:23552
	global_load_lds_dwordx4 v128, s[34:35]
	s_mov_b32 m0, s40
	s_nop 0
	global_load_lds_dwordx4 v132, s[34:35]
	s_barrier
	s_waitcnt lgkmcnt(0)
	s_setprio 1
	s_waitcnt lgkmcnt(0)
	v_mfma_f32_16x16x32_bf16 v[60:63], v[144:147], v[170:173], v[60:63]
	v_mfma_f32_16x16x32_bf16 v[56:59], v[162:165], v[170:173], v[56:59]
	v_mfma_f32_16x16x32_bf16 v[44:47], v[144:147], v[178:181], v[44:47]
	v_mfma_f32_16x16x32_bf16 v[40:43], v[162:165], v[178:181], v[40:43]
	v_mfma_f32_16x16x32_bf16 v[28:31], v[144:147], v[194:197], v[28:31]
	v_mfma_f32_16x16x32_bf16 v[24:27], v[162:165], v[194:197], v[24:27]
	v_mfma_f32_16x16x32_bf16 v[12:15], v[144:147], v[202:205], v[12:15]
	v_mfma_f32_16x16x32_bf16 v[8:11], v[162:165], v[202:205], v[8:11]
	v_mfma_f32_16x16x32_bf16 v[60:63], v[148:151], v[174:177], v[60:63]
	v_mfma_f32_16x16x32_bf16 v[56:59], v[166:169], v[174:177], v[56:59]
	v_mfma_f32_16x16x32_bf16 v[44:47], v[148:151], v[186:189], v[44:47]
	v_mfma_f32_16x16x32_bf16 v[40:43], v[166:169], v[186:189], v[40:43]
	v_mfma_f32_16x16x32_bf16 v[28:31], v[148:151], v[198:201], v[28:31]
	v_mfma_f32_16x16x32_bf16 v[24:27], v[166:169], v[198:201], v[24:27]
	v_mfma_f32_16x16x32_bf16 v[12:15], v[148:151], v[206:209], v[12:15]
	v_mfma_f32_16x16x32_bf16 v[8:11], v[166:169], v[206:209], v[8:11]
	s_setprio 0
	s_barrier
	s_add_u32 s56, s30, 0x80000
	s_addc_u32 s57, s31, 0
	s_add_i32 s55, s49, s38
	s_mov_b32 m0, s55
	s_nop 0
	global_load_lds_dwordx4 v130, s[56:57]
	s_add_i32 m0, s55, 0x2000
	s_nop 0
	global_load_lds_dwordx4 v134, s[56:57]
	s_waitcnt vmcnt(6)
	s_barrier
	s_setprio 1
	v_mfma_f32_16x16x32_bf16 v[52:55], v[210:213], v[170:173], v[52:55]
	v_mfma_f32_16x16x32_bf16 v[48:51], v[218:221], v[170:173], v[48:51]
	v_mfma_f32_16x16x32_bf16 v[36:39], v[210:213], v[178:181], v[36:39]
	v_mfma_f32_16x16x32_bf16 v[32:35], v[218:221], v[178:181], v[32:35]
	v_mfma_f32_16x16x32_bf16 v[20:23], v[210:213], v[194:197], v[20:23]
	v_mfma_f32_16x16x32_bf16 v[16:19], v[218:221], v[194:197], v[16:19]
	v_mfma_f32_16x16x32_bf16 v[4:7], v[210:213], v[202:205], v[4:7]
	v_mfma_f32_16x16x32_bf16 v[0:3], v[218:221], v[202:205], v[0:3]
	v_mfma_f32_16x16x32_bf16 v[52:55], v[214:217], v[174:177], v[52:55]
	v_mfma_f32_16x16x32_bf16 v[48:51], v[222:225], v[174:177], v[48:51]
	v_mfma_f32_16x16x32_bf16 v[36:39], v[214:217], v[186:189], v[36:39]
	v_mfma_f32_16x16x32_bf16 v[32:35], v[222:225], v[186:189], v[32:35]
	v_mfma_f32_16x16x32_bf16 v[20:23], v[214:217], v[198:201], v[20:23]
	v_mfma_f32_16x16x32_bf16 v[16:19], v[222:225], v[198:201], v[16:19]
	v_mfma_f32_16x16x32_bf16 v[4:7], v[214:217], v[206:209], v[4:7]
	v_mfma_f32_16x16x32_bf16 v[0:3], v[222:225], v[206:209], v[0:3]
	s_setprio 0
	s_add_i32 s55, 0, 0x18000
	v_add_u32_e32 v161, s55, v155
	s_barrier
	ds_read_b128 v[144:147], v161
	ds_read_b128 v[148:151], v161 offset:1024
	ds_read_b128 v[162:165], v161 offset:2048
	ds_read_b128 v[166:169], v161 offset:3072
	s_add_u32 s34, s34, 0x80000
	s_addc_u32 s35, s35, 0
	s_mov_b32 m0, s41
	ds_read_b128 v[170:173], v158 offset:32768
	ds_read_b128 v[174:177], v158 offset:33792
	ds_read_b128 v[178:181], v158 offset:34816
	ds_read_b128 v[186:189], v158 offset:35840
	ds_read_b128 v[194:197], v158 offset:36864
	ds_read_b128 v[198:201], v158 offset:37888
	ds_read_b128 v[202:205], v158 offset:38912
	ds_read_b128 v[206:209], v158 offset:39936
	global_load_lds_dwordx4 v128, s[34:35]
	s_mov_b32 m0, s42
	s_nop 0
	global_load_lds_dwordx4 v132, s[34:35]
	s_waitcnt lgkmcnt(8)
	s_barrier
	s_waitcnt lgkmcnt(0)
	s_setprio 1
	s_waitcnt lgkmcnt(0)
	v_mfma_f32_16x16x32_bf16 v[124:127], v[144:147], v[170:173], v[124:127]
	v_mfma_f32_16x16x32_bf16 v[120:123], v[162:165], v[170:173], v[120:123]
	v_mfma_f32_16x16x32_bf16 v[108:111], v[144:147], v[178:181], v[108:111]
	v_mfma_f32_16x16x32_bf16 v[104:107], v[162:165], v[178:181], v[104:107]
	v_mfma_f32_16x16x32_bf16 v[92:95], v[144:147], v[194:197], v[92:95]
	v_mfma_f32_16x16x32_bf16 v[88:91], v[162:165], v[194:197], v[88:91]
	v_mfma_f32_16x16x32_bf16 v[76:79], v[144:147], v[202:205], v[76:79]
	v_mfma_f32_16x16x32_bf16 v[72:75], v[162:165], v[202:205], v[72:75]
	v_mfma_f32_16x16x32_bf16 v[124:127], v[148:151], v[174:177], v[124:127]
	v_mfma_f32_16x16x32_bf16 v[120:123], v[166:169], v[174:177], v[120:123]
	v_mfma_f32_16x16x32_bf16 v[108:111], v[148:151], v[186:189], v[108:111]
	v_mfma_f32_16x16x32_bf16 v[104:107], v[166:169], v[186:189], v[104:107]
	v_mfma_f32_16x16x32_bf16 v[92:95], v[148:151], v[198:201], v[92:95]
	v_mfma_f32_16x16x32_bf16 v[88:91], v[166:169], v[198:201], v[88:91]
	v_mfma_f32_16x16x32_bf16 v[76:79], v[148:151], v[206:209], v[76:79]
	v_mfma_f32_16x16x32_bf16 v[72:75], v[166:169], v[206:209], v[72:75]
	s_setprio 0
	s_barrier
	s_add_i32 s34, 0, 0x1c000
	s_add_i32 s35, s55, s38
	v_add_u32_e32 v161, s34, v155
	s_mov_b32 m0, s35
	ds_read_b128 v[210:213], v161
	ds_read_b128 v[214:217], v161 offset:1024
	ds_read_b128 v[218:221], v161 offset:2048
	ds_read_b128 v[222:225], v161 offset:3072
	global_load_lds_dwordx4 v130, s[58:59]
	s_add_i32 m0, s35, 0x2000
	s_nop 0
	global_load_lds_dwordx4 v134, s[58:59]
	s_barrier
	s_waitcnt lgkmcnt(0)
	s_setprio 1
	s_waitcnt lgkmcnt(0)
	v_mfma_f32_16x16x32_bf16 v[116:119], v[210:213], v[170:173], v[116:119]
	v_mfma_f32_16x16x32_bf16 v[112:115], v[218:221], v[170:173], v[112:115]
	v_mfma_f32_16x16x32_bf16 v[100:103], v[210:213], v[178:181], v[100:103]
	v_mfma_f32_16x16x32_bf16 v[96:99], v[218:221], v[178:181], v[96:99]
	v_mfma_f32_16x16x32_bf16 v[84:87], v[210:213], v[194:197], v[84:87]
	v_mfma_f32_16x16x32_bf16 v[80:83], v[218:221], v[194:197], v[80:83]
	v_mfma_f32_16x16x32_bf16 v[68:71], v[210:213], v[202:205], v[68:71]
	v_mfma_f32_16x16x32_bf16 v[64:67], v[218:221], v[202:205], v[64:67]
	v_mfma_f32_16x16x32_bf16 v[116:119], v[214:217], v[174:177], v[116:119]
	v_mfma_f32_16x16x32_bf16 v[112:115], v[222:225], v[174:177], v[112:115]
	v_mfma_f32_16x16x32_bf16 v[100:103], v[214:217], v[186:189], v[100:103]
	v_mfma_f32_16x16x32_bf16 v[96:99], v[222:225], v[186:189], v[96:99]
	v_mfma_f32_16x16x32_bf16 v[84:87], v[214:217], v[198:201], v[84:87]
	v_mfma_f32_16x16x32_bf16 v[80:83], v[222:225], v[198:201], v[80:83]
	v_mfma_f32_16x16x32_bf16 v[68:71], v[214:217], v[206:209], v[68:71]
	v_mfma_f32_16x16x32_bf16 v[64:67], v[222:225], v[206:209], v[64:67]
	s_setprio 0
	s_mov_b32 m0, s44
	s_barrier
; __device__ __forceinline__ unsigned pk2(float lo, float hi) { unsigned r; asm("v_cvt_pk_bf16_f32 %0, %1, %2" : "=v"(r) : "v"(lo), "v"(hi)); return r; }
; template <class Epi>
; __device__ __forceinline__ void gemm_phase(LAS unsigned char* lds, const GemmD g, const Epi& E) {
;     ...
;         for (int t = 0; t < nt; t += 2) PG8_KITER(t);
;     __device__ __forceinline__ void operator()(const f32x4 (&acc)[2][2][4][2], const Unit& u, int wr, int wc, int fr, int fq) const {
;         const int row0 = u.pm * BM + wr * 64 + fr, col0 = u.pn * BM + wc * 32 + 8 * fq;
;         const bool sig = (u.pn >= 36 && u.pn < 52), isdt = (u.pn == 52);
; #pragma unroll
;         for (int ai = 0; ai < 2; ++ai)
; #pragma unroll
;             for (int m = 0; m < 4; ++m) { const int row = row0 + ai * HALF + m * 16;
; #pragma unroll
;                 for (int bj = 0; bj < 2; ++bj) { const f32x4 v0 = acc[ai][bj][m][0], v1 = acc[ai][bj][m][1]; const int col = col0 + bj * HALF;
;                     if (sig) {
;                         const int c = (col - C_GS) >> 1;
;                         float ra[4], gp[4];
; #pragma unroll
;                         for (int j = 0; j < 4; ++j) { const float ea = __expf(-fminf(fmaxf(v0[j], -30.f), 30.f)), eb = __expf(-fminf(fmaxf(v1[j], -30.f), 30.f)); gp[j] = __builtin_amdgcn_rcpf(1.0f + eb); ra[j] = (1.0f + eb) * __builtin_amdgcn_rcpf(1.0f + ea); }
;                         u32x2 wr_, wg; wr_.x = pk2(ra[0], ra[1]); wr_.y = pk2(ra[2], ra[3]); wg.x = pk2(gp[0], gp[1]); wg.y = pk2(gp[2], gp[3]);
;                         *(u32x2*)(proj + (size_t)row * NPROJ + C_GS + c) = wr_;
;                         *(u32x2*)(proj + (size_t)row * NPROJ + C_GP + c) = wg;
;                     } else {
;                         u32x4 w; w.x = pk2(v0[0], v0[1]); w.y = pk2(v0[2], v0[3]); w.z = pk2(v1[0], v1[1]); w.w = pk2(v1[2], v1[3]);
;                         *(u32x4*)(proj + (size_t)row * NPROJ + col) = w;
;                         if (isdt && col < C_DT + 32) { float* d = dtraw + (size_t)row * 32 + (col - C_DT); *(f32x4*)d = v0; *(f32x4*)(d + 4) = v1; } } } }
	ds_read_b128 v[170:173], v158 offset:49152
	ds_read_b128 v[174:177], v158 offset:50176
	ds_read_b128 v[178:181], v158 offset:51200
	ds_read_b128 v[186:189], v158 offset:52224
	ds_read_b128 v[194:197], v158 offset:53248
	ds_read_b128 v[198:201], v158 offset:54272
	ds_read_b128 v[202:205], v158 offset:55296
	ds_read_b128 v[206:209], v158 offset:56320
	global_load_lds_dwordx4 v128, s[60:61]
	s_mov_b32 m0, s45
	s_nop 0
	global_load_lds_dwordx4 v132, s[60:61]
	s_barrier
	s_waitcnt lgkmcnt(0)
	s_setprio 1
	s_waitcnt lgkmcnt(0)
	v_mfma_f32_16x16x32_bf16 v[60:63], v[144:147], v[170:173], v[60:63]
	v_mfma_f32_16x16x32_bf16 v[56:59], v[162:165], v[170:173], v[56:59]
	v_mfma_f32_16x16x32_bf16 v[44:47], v[144:147], v[178:181], v[44:47]
	v_mfma_f32_16x16x32_bf16 v[40:43], v[162:165], v[178:181], v[40:43]
	v_mfma_f32_16x16x32_bf16 v[28:31], v[144:147], v[194:197], v[28:31]
	v_mfma_f32_16x16x32_bf16 v[24:27], v[162:165], v[194:197], v[24:27]
	v_mfma_f32_16x16x32_bf16 v[12:15], v[144:147], v[202:205], v[12:15]
	v_mfma_f32_16x16x32_bf16 v[8:11], v[162:165], v[202:205], v[8:11]
	v_mfma_f32_16x16x32_bf16 v[60:63], v[148:151], v[174:177], v[60:63]
	v_mfma_f32_16x16x32_bf16 v[56:59], v[166:169], v[174:177], v[56:59]
	v_mfma_f32_16x16x32_bf16 v[44:47], v[148:151], v[186:189], v[44:47]
	v_mfma_f32_16x16x32_bf16 v[40:43], v[166:169], v[186:189], v[40:43]
	v_mfma_f32_16x16x32_bf16 v[28:31], v[148:151], v[198:201], v[28:31]
	v_mfma_f32_16x16x32_bf16 v[24:27], v[166:169], v[198:201], v[24:27]
	v_mfma_f32_16x16x32_bf16 v[12:15], v[148:151], v[206:209], v[12:15]
	v_mfma_f32_16x16x32_bf16 v[8:11], v[166:169], v[206:209], v[8:11]
	s_setprio 0
	s_barrier
	s_add_u32 s30, s30, 0x80080
	s_addc_u32 s31, s31, 0
	s_add_i32 s34, s34, s38
	s_mov_b32 m0, s34
	s_nop 0
	global_load_lds_dwordx4 v130, s[30:31]
	s_add_i32 m0, s34, 0x2000
	s_nop 0
	global_load_lds_dwordx4 v134, s[30:31]
	s_waitcnt vmcnt(6)
	s_barrier
	s_setprio 1
	v_mfma_f32_16x16x32_bf16 v[52:55], v[210:213], v[170:173], v[52:55]
	v_mfma_f32_16x16x32_bf16 v[48:51], v[218:221], v[170:173], v[48:51]
	v_mfma_f32_16x16x32_bf16 v[36:39], v[210:213], v[178:181], v[36:39]
	v_mfma_f32_16x16x32_bf16 v[32:35], v[218:221], v[178:181], v[32:35]
	v_mfma_f32_16x16x32_bf16 v[20:23], v[210:213], v[194:197], v[20:23]
	v_mfma_f32_16x16x32_bf16 v[16:19], v[218:221], v[194:197], v[16:19]
	v_mfma_f32_16x16x32_bf16 v[4:7], v[210:213], v[202:205], v[4:7]
	v_mfma_f32_16x16x32_bf16 v[0:3], v[218:221], v[202:205], v[0:3]
	v_mfma_f32_16x16x32_bf16 v[52:55], v[214:217], v[174:177], v[52:55]
	v_mfma_f32_16x16x32_bf16 v[48:51], v[222:225], v[174:177], v[48:51]
	v_mfma_f32_16x16x32_bf16 v[36:39], v[214:217], v[186:189], v[36:39]
	v_mfma_f32_16x16x32_bf16 v[32:35], v[222:225], v[186:189], v[32:35]
	v_mfma_f32_16x16x32_bf16 v[20:23], v[214:217], v[198:201], v[20:23]
	v_mfma_f32_16x16x32_bf16 v[16:19], v[222:225], v[198:201], v[16:19]
	v_mfma_f32_16x16x32_bf16 v[4:7], v[214:217], v[206:209], v[4:7]
	v_mfma_f32_16x16x32_bf16 v[0:3], v[222:225], v[206:209], v[0:3]
	s_setprio 0
	s_add_i32 s54, s54, 2
	s_add_u32 s28, s28, 0x100
	s_addc_u32 s29, s29, 0
	s_add_u32 s11, s11, 0x100
	s_addc_u32 s27, s27, 0
	s_cmp_gt_u32 s54, 29
	s_barrier
	s_cbranch_scc0 .LBB0_181
	s_sub_i32 s2, s6, 36
	v_lshl_add_u32 v146, s26, 8, v154
	s_cmp_gt_u32 s2, 15
	s_cselect_b64 s[28:29], -1, 0
	s_cmp_eq_u32 s6, 52
	v_ashrrev_i32_e32 v147, 31, v146
	v_mad_i64_i32 v[152:153], s[2:3], v146, s50, 0
	v_lshl_or_b32 v144, s6, 8, v156
	s_cselect_b64 s[26:27], -1, 0
	v_lshlrev_b64 v[150:151], 7, v[146:147]
	s_mov_b64 s[2:3], -1
	s_and_b64 vcc, exec, s[28:29]
	s_cbranch_vccz .LBB0_186
	v_lshl_add_u64 v[148:149], s[92:93], 0, v[152:153]
	v_ashrrev_i32_e32 v145, 31, v144
	v_cmp_gt_i32_e32 vcc, s52, v144
	v_lshl_add_u64 v[148:149], v[144:145], 1, v[148:149]
	s_and_b64 s[2:3], s[26:27], vcc
	v_cvt_pk_bf16_f32 v162, v124, v125
	v_cvt_pk_bf16_f32 v163, v126, v127
	v_cvt_pk_bf16_f32 v164, v120, v121
	v_cvt_pk_bf16_f32 v165, v122, v123
	global_store_dwordx4 v[148:149], v[162:165], off
	s_and_saveexec_b64 s[6:7], s[2:3]
	s_cbranch_execz .LBB0_185
	v_lshl_add_u64 v[148:149], s[14:15], 0, v[150:151]
	v_lshl_add_u64 v[148:149], v[144:145], 2, v[148:149]
	v_add_co_u32_e32 v162, vcc, 0xffff3000, v148
	s_nop 1
	v_addc_co_u32_e32 v163, vcc, -1, v149, vcc
	v_add_co_u32_e32 v148, vcc, 0xffff4000, v148
	global_store_dwordx4 v[162:163], v[124:127], off
	s_nop 0
	v_addc_co_u32_e32 v149, vcc, -1, v149, vcc
	global_store_dwordx4 v[148:149], v[120:123], off offset:-4080
